# MLA fast path v3: as v2 plus own staged-tile LDS writes and next-tile loads under the PV MFMAs and own loop back-edge for consecutive full super-tiles
# speedup vs baseline: 1.0281x; 1.0084x over previous
.Lmla_l0_negm_ok:
	s_nop 1
	s_waitcnt lgkmcnt(3)
	v_mfma_f32_32x32x16_bf16 v[64:79], v[2:5], v[92:95], v[124:139]
	ds_read_b128 v[234:237], v14 offset:128
	s_waitcnt lgkmcnt(3)
	v_mfma_f32_32x32x16_bf16 v[64:79], v[6:9], v[96:99], v[64:79]
	ds_read_b128 v[240:243], v14 offset:160
	s_waitcnt lgkmcnt(3)
	v_mfma_f32_32x32x16_bf16 v[64:79], v[10:13], v[100:103], v[64:79]
	ds_read_b128 v[2:5], v14 offset:6656
	s_waitcnt lgkmcnt(3)
	v_mfma_f32_32x32x16_bf16 v[64:79], v[140:143], v[104:107], v[64:79]
	ds_read_b128 v[6:9], v14 offset:6688
	s_waitcnt lgkmcnt(3)
	v_mfma_f32_32x32x16_bf16 v[64:79], v[234:237], v[116:119], v[64:79]
	ds_read_b128 v[10:13], v14 offset:6720
	s_waitcnt lgkmcnt(3)
	v_mfma_f32_32x32x16_bf16 v[64:79], v[240:243], v[120:123], v[64:79]
	ds_read_b128 v[140:143], v14 offset:6752
	s_waitcnt lgkmcnt(3)
	v_mfma_f32_32x32x16_bf16 v[48:63], v[2:5], v[92:95], v[124:139]
	ds_read_b128 v[234:237], v14 offset:6784
	s_waitcnt lgkmcnt(3)
	v_mfma_f32_32x32x16_bf16 v[48:63], v[6:9], v[96:99], v[48:63]
	ds_read_b128 v[240:243], v14 offset:6816
	s_waitcnt lgkmcnt(3)
	v_mfma_f32_32x32x16_bf16 v[48:63], v[10:13], v[100:103], v[48:63]
	ds_read_b128 v[2:5], v14 offset:21504
	s_waitcnt lgkmcnt(3)
	v_mfma_f32_32x32x16_bf16 v[48:63], v[140:143], v[104:107], v[48:63]
	ds_read_b128 v[6:9], v14 offset:21536
	s_waitcnt lgkmcnt(3)
	v_mfma_f32_32x32x16_bf16 v[48:63], v[234:237], v[116:119], v[48:63]
	ds_read_b128 v[10:13], v14 offset:21568
	s_waitcnt lgkmcnt(3)
	v_mfma_f32_32x32x16_bf16 v[48:63], v[240:243], v[120:123], v[48:63]
	ds_read_b128 v[140:143], v14 offset:21600
	v_exp_f32_e32 v64, v64
	v_exp_f32_e32 v65, v65
	s_waitcnt lgkmcnt(3)
	v_mfma_f32_32x32x16_bf16 v[202:217], v[2:5], v[92:95], v[124:139]
	ds_read_b128 v[234:237], v14 offset:21632
	v_exp_f32_e32 v66, v66
	v_exp_f32_e32 v67, v67
	v_exp_f32_e32 v68, v68
	v_exp_f32_e32 v69, v69
	v_exp_f32_e32 v70, v70
	s_waitcnt lgkmcnt(3)
	v_mfma_f32_32x32x16_bf16 v[202:217], v[6:9], v[96:99], v[202:217]
	ds_read_b128 v[240:243], v14 offset:21664
	v_exp_f32_e32 v71, v71
	v_pk_add_f32 v[246:247], v[64:65], v[66:67]
	v_exp_f32_e32 v72, v72
	v_exp_f32_e32 v73, v73
	v_exp_f32_e32 v74, v74
	s_waitcnt lgkmcnt(3)
	v_mfma_f32_32x32x16_bf16 v[202:217], v[10:13], v[100:103], v[202:217]
	ds_read_b128 v[2:5], v14 offset:28160
	v_exp_f32_e32 v75, v75
	v_pk_add_f32 v[248:249], v[68:69], v[70:71]
	v_exp_f32_e32 v76, v76
	v_exp_f32_e32 v77, v77
	v_pk_add_f32 v[246:247], v[246:247], v[72:73]
	s_waitcnt lgkmcnt(3)
	v_mfma_f32_32x32x16_bf16 v[202:217], v[140:143], v[104:107], v[202:217]
	ds_read_b128 v[6:9], v14 offset:28192
	v_exp_f32_e32 v78, v78
	v_exp_f32_e32 v79, v79
	v_pk_add_f32 v[248:249], v[248:249], v[74:75]
	v_exp_f32_e32 v48, v48
	v_exp_f32_e32 v49, v49
	s_waitcnt lgkmcnt(3)
	v_mfma_f32_32x32x16_bf16 v[202:217], v[234:237], v[116:119], v[202:217]
	ds_read_b128 v[10:13], v14 offset:28224
	v_pk_add_f32 v[246:247], v[246:247], v[76:77]
	v_exp_f32_e32 v50, v50
	v_exp_f32_e32 v51, v51
	v_pk_add_f32 v[248:249], v[248:249], v[78:79]
	v_exp_f32_e32 v52, v52
	s_waitcnt lgkmcnt(3)
	v_mfma_f32_32x32x16_bf16 v[202:217], v[240:243], v[120:123], v[202:217]
	ds_read_b128 v[140:143], v14 offset:28256
	v_exp_f32_e32 v53, v53
	v_pk_add_f32 v[246:247], v[246:247], v[48:49]
	v_exp_f32_e32 v54, v54
	v_exp_f32_e32 v55, v55
	v_pk_add_f32 v[248:249], v[248:249], v[50:51]
	s_waitcnt lgkmcnt(3)
	v_mfma_f32_32x32x16_bf16 v[218:233], v[2:5], v[92:95], v[124:139]
	ds_read_b128 v[234:237], v14 offset:28288
	v_exp_f32_e32 v56, v56
	v_exp_f32_e32 v57, v57
	v_pk_add_f32 v[246:247], v[246:247], v[52:53]
	v_exp_f32_e32 v58, v58
	v_exp_f32_e32 v59, v59
	s_waitcnt lgkmcnt(3)
	v_mfma_f32_32x32x16_bf16 v[218:233], v[6:9], v[96:99], v[218:233]
	ds_read_b128 v[240:243], v14 offset:28320
	v_pk_add_f32 v[248:249], v[248:249], v[54:55]
	v_exp_f32_e32 v60, v60
	v_exp_f32_e32 v61, v61
	v_pk_add_f32 v[246:247], v[246:247], v[56:57]
	v_exp_f32_e32 v62, v62
	s_waitcnt lgkmcnt(3)
	v_mfma_f32_32x32x16_bf16 v[218:233], v[10:13], v[100:103], v[218:233]
	ds_read_b64_tr_b16 v[2:3], v0 offset:13312
	ds_read_b64_tr_b16 v[4:5], v0 offset:13824
	v_exp_f32_e32 v63, v63
	v_pk_add_f32 v[248:249], v[248:249], v[58:59]
	v_pk_add_f32 v[246:247], v[246:247], v[60:61]
	v_pk_add_f32 v[248:249], v[248:249], v[62:63]
	v_pk_add_f32 v[246:247], v[246:247], v[248:249]
	s_waitcnt lgkmcnt(4)
	v_mfma_f32_32x32x16_bf16 v[218:233], v[140:143], v[104:107], v[218:233]
	ds_read_b64_tr_b16 v[6:7], v0 offset:17408
	ds_read_b64_tr_b16 v[8:9], v0 offset:17920
	v_add_f32_e32 v250, v246, v247
	v_cmp_ngt_f32_e32 vcc, 0x43800000, v250
	s_cbranch_vccnz .Lmla_l0_fbA
	v_add_f32_e32 v200, v200, v250
	v_cvt_pk_bf16_f32 v64, v64, v65
	v_cvt_pk_bf16_f32 v65, v66, v67
	s_waitcnt lgkmcnt(5)
	v_mfma_f32_32x32x16_bf16 v[218:233], v[234:237], v[116:119], v[218:233]
	ds_read_b64_tr_b16 v[10:11], v0 offset:14336
	ds_read_b64_tr_b16 v[12:13], v0 offset:14848
	v_cvt_pk_bf16_f32 v66, v68, v69
	v_cvt_pk_bf16_f32 v67, v70, v71
	v_cvt_pk_bf16_f32 v68, v72, v73
	v_cvt_pk_bf16_f32 v69, v74, v75
	v_cvt_pk_bf16_f32 v70, v76, v77
	s_waitcnt lgkmcnt(6)
	v_mfma_f32_32x32x16_bf16 v[218:233], v[240:243], v[120:123], v[218:233]
	ds_read_b64_tr_b16 v[140:141], v0 offset:18432
	ds_read_b64_tr_b16 v[142:143], v0 offset:18944
	v_cvt_pk_bf16_f32 v71, v78, v79
	v_cvt_pk_bf16_f32 v48, v48, v49
	v_cvt_pk_bf16_f32 v49, v50, v51
	v_cvt_pk_bf16_f32 v50, v52, v53
	v_cvt_pk_bf16_f32 v51, v54, v55
	v_cvt_pk_bf16_f32 v52, v56, v57
	v_cvt_pk_bf16_f32 v53, v58, v59
	v_cvt_pk_bf16_f32 v54, v60, v61
	v_cvt_pk_bf16_f32 v55, v62, v63
	v_exp_f32_e32 v202, v202
	v_exp_f32_e32 v203, v203
	s_waitcnt lgkmcnt(6)
	v_mfma_f32_32x32x16_bf16 v[32:47], v[2:5], v[64:67], v[32:47]
	ds_read_b64_tr_b16 v[234:235], v0 offset:15360
	ds_read_b64_tr_b16 v[236:237], v0 offset:15872
	v_exp_f32_e32 v204, v204
	v_exp_f32_e32 v205, v205
	v_exp_f32_e32 v206, v206
	v_exp_f32_e32 v207, v207
	v_exp_f32_e32 v208, v208
	s_waitcnt lgkmcnt(6)
	v_mfma_f32_32x32x16_bf16 v[16:31], v[6:9], v[64:67], v[16:31]
	ds_read_b64_tr_b16 v[240:241], v0 offset:19456
	ds_read_b64_tr_b16 v[242:243], v0 offset:19968
	v_exp_f32_e32 v209, v209
	v_pk_add_f32 v[246:247], v[202:203], v[204:205]
	v_exp_f32_e32 v210, v210
	v_exp_f32_e32 v211, v211
	v_exp_f32_e32 v212, v212
	s_waitcnt lgkmcnt(6)
	v_mfma_f32_32x32x16_bf16 v[32:47], v[10:13], v[68:71], v[32:47]
	ds_read_b64_tr_b16 v[2:3], v0 offset:16384
	ds_read_b64_tr_b16 v[4:5], v0 offset:16896
	v_exp_f32_e32 v213, v213
	v_pk_add_f32 v[248:249], v[206:207], v[208:209]
	v_exp_f32_e32 v214, v214
	v_exp_f32_e32 v215, v215
	v_pk_add_f32 v[246:247], v[246:247], v[210:211]
	s_waitcnt lgkmcnt(6)
	v_mfma_f32_32x32x16_bf16 v[16:31], v[140:143], v[68:71], v[16:31]
	ds_read_b64_tr_b16 v[6:7], v0 offset:20480
	ds_read_b64_tr_b16 v[8:9], v0 offset:20992
	v_exp_f32_e32 v216, v216
	v_exp_f32_e32 v217, v217
	v_pk_add_f32 v[248:249], v[248:249], v[212:213]
	v_exp_f32_e32 v218, v218
	v_exp_f32_e32 v219, v219
	s_waitcnt lgkmcnt(6)
	v_mfma_f32_32x32x16_bf16 v[32:47], v[234:237], v[48:51], v[32:47]
	ds_read_b64_tr_b16 v[10:11], v0 offset:34816
	ds_read_b64_tr_b16 v[12:13], v0 offset:35328
	v_pk_add_f32 v[246:247], v[246:247], v[214:215]
	v_exp_f32_e32 v220, v220
	v_exp_f32_e32 v221, v221
	v_pk_add_f32 v[248:249], v[248:249], v[216:217]
	v_exp_f32_e32 v222, v222
	s_waitcnt lgkmcnt(6)
	v_mfma_f32_32x32x16_bf16 v[16:31], v[240:243], v[48:51], v[16:31]
	ds_read_b64_tr_b16 v[140:141], v0 offset:38912
	ds_read_b64_tr_b16 v[142:143], v0 offset:39424
	v_exp_f32_e32 v223, v223
	v_pk_add_f32 v[246:247], v[246:247], v[218:219]
	v_exp_f32_e32 v224, v224
	v_exp_f32_e32 v225, v225
	v_pk_add_f32 v[248:249], v[248:249], v[220:221]
	s_waitcnt lgkmcnt(6)
	v_mfma_f32_32x32x16_bf16 v[32:47], v[2:5], v[52:55], v[32:47]
	ds_read_b64_tr_b16 v[234:235], v0 offset:35840
	ds_read_b64_tr_b16 v[236:237], v0 offset:36352
	v_exp_f32_e32 v226, v226
	v_exp_f32_e32 v227, v227
	v_pk_add_f32 v[246:247], v[246:247], v[222:223]
	v_exp_f32_e32 v228, v228
	v_exp_f32_e32 v229, v229
	s_waitcnt lgkmcnt(6)
	v_mfma_f32_32x32x16_bf16 v[16:31], v[6:9], v[52:55], v[16:31]
	ds_read_b64_tr_b16 v[240:241], v0 offset:39936
	ds_read_b64_tr_b16 v[242:243], v0 offset:40448
	v_pk_add_f32 v[248:249], v[248:249], v[224:225]
	v_exp_f32_e32 v230, v230
	v_exp_f32_e32 v231, v231
	v_pk_add_f32 v[246:247], v[246:247], v[226:227]
	v_exp_f32_e32 v232, v232
	v_exp_f32_e32 v233, v233
	v_pk_add_f32 v[248:249], v[248:249], v[228:229]
	v_pk_add_f32 v[246:247], v[246:247], v[230:231]
	v_pk_add_f32 v[248:249], v[248:249], v[232:233]
	v_pk_add_f32 v[246:247], v[246:247], v[248:249]
	v_add_f32_e32 v250, v246, v247
	v_cmp_ngt_f32_e32 vcc, 0x43800000, v250
	s_cbranch_vccnz .Lmla_l0_fbB
	v_add_f32_e32 v200, v200, v250
	v_cvt_pk_bf16_f32 v202, v202, v203
	v_cvt_pk_bf16_f32 v203, v204, v205
	v_cvt_pk_bf16_f32 v204, v206, v207
	v_cvt_pk_bf16_f32 v205, v208, v209
	v_cvt_pk_bf16_f32 v206, v210, v211
	v_cvt_pk_bf16_f32 v207, v212, v213
	v_cvt_pk_bf16_f32 v208, v214, v215
	v_cvt_pk_bf16_f32 v209, v216, v217
	v_cvt_pk_bf16_f32 v218, v218, v219
	v_cvt_pk_bf16_f32 v219, v220, v221
	v_cvt_pk_bf16_f32 v220, v222, v223
	v_cvt_pk_bf16_f32 v221, v224, v225
	v_cvt_pk_bf16_f32 v222, v226, v227
	v_cvt_pk_bf16_f32 v223, v228, v229
	v_cvt_pk_bf16_f32 v224, v230, v231
	v_cvt_pk_bf16_f32 v225, v232, v233
	s_waitcnt lgkmcnt(6)
	v_mfma_f32_32x32x16_bf16 v[32:47], v[10:13], v[202:205], v[32:47]
	ds_read_b64_tr_b16 v[2:3], v0 offset:36864
	ds_read_b64_tr_b16 v[4:5], v0 offset:37376
	s_waitcnt vmcnt(0)
	s_xor_b32 s16, s18, 1
	s_mul_i32 s16, s16, 0xa800
	v_add_u32_e32 v254, s16, v170
	s_mov_b64 exec, s[2:3]
	v_add_u32_e32 v254, v254, v149
	v_add3_u32 v254, v254, v171, v169
	v_add_u32_e32 v254, 0x1c00, v254
	s_not_b64 exec, exec
	v_add3_u32 v254, v254, v192, v193
	s_mov_b64 exec, -1
	ds_write_b128 v254, v[80:83]
	v_add_u32_e32 v254, s16, v172
	s_mov_b64 exec, s[4:5]
	v_add_u32_e32 v254, v254, v149
	v_add3_u32 v254, v254, v173, v169
	v_add_u32_e32 v254, 0x1c00, v254
	s_not_b64 exec, exec
	v_add3_u32 v254, v254, v194, v195
	s_mov_b64 exec, -1
	ds_write_b128 v254, v[84:87]
	v_add_u32_e32 v254, s16, v174
	s_mov_b64 exec, s[6:7]
	v_add_u32_e32 v254, v254, v149
	v_add3_u32 v254, v254, v175, v169
	v_add_u32_e32 v254, 0x1c00, v254
	s_not_b64 exec, exec
	v_add3_u32 v254, v254, v196, v197
	s_mov_b64 exec, -1
	ds_write_b128 v254, v[88:91]
	v_add_u32_e32 v254, s16, v176
	s_mov_b64 exec, s[8:9]
	v_add_u32_e32 v254, v254, v149
	v_add3_u32 v254, v254, v177, v169
	v_add_u32_e32 v254, 0x1c00, v254
	s_not_b64 exec, exec
	v_add3_u32 v254, v254, v198, v199
	s_mov_b64 exec, -1
	ds_write_b128 v254, v[108:111]
	v_add_u32_e32 v254, s16, v178
	s_mov_b64 exec, s[10:11]
	v_add_u32_e32 v254, v254, v149
	v_add3_u32 v254, v254, v179, v169
	v_add_u32_e32 v254, 0x1c00, v254
	s_not_b64 exec, exec
	v_add3_u32 v254, v254, v180, v181
	s_mov_b64 exec, -1
	ds_write_b128 v254, v[112:115]
	s_waitcnt lgkmcnt(11)
	v_mfma_f32_32x32x16_bf16 v[16:31], v[140:143], v[202:205], v[16:31]
	ds_read_b64_tr_b16 v[6:7], v0 offset:40960
	ds_read_b64_tr_b16 v[8:9], v0 offset:41472
	s_waitcnt lgkmcnt(11)
	v_mfma_f32_32x32x16_bf16 v[32:47], v[234:237], v[206:209], v[32:47]
	ds_read_b64_tr_b16 v[10:11], v0 offset:37888
	ds_read_b64_tr_b16 v[12:13], v0 offset:38400
	s_waitcnt lgkmcnt(11)
	v_mfma_f32_32x32x16_bf16 v[16:31], v[240:243], v[206:209], v[16:31]
	ds_read_b64_tr_b16 v[140:141], v0 offset:41984
	ds_read_b64_tr_b16 v[142:143], v0 offset:42496
	s_waitcnt lgkmcnt(11)
	v_mfma_f32_32x32x16_bf16 v[32:47], v[2:5], v[218:221], v[32:47]
	s_waitcnt lgkmcnt(4)
	v_mfma_f32_32x32x16_bf16 v[16:31], v[6:9], v[218:221], v[16:31]
	s_add_i32 s0, s19, 0xc0
	s_cmp_le_i32 s0, s67
	s_cbranch_scc0 .Lmla_l0_noload
	s_add_u32 s16, s12, 0x30000
	s_addc_u32 s17, s13, 0
	s_add_i32 s0, s76, 1
	s_lshl_b32 s0, s0, 1
	v_mov_b32_e32 v255, 0
	s_mov_b64 exec, s[2:3]
	v_or_b32_e32 v254, s0, v186
	v_lshl_add_u32 v254, v254, 6, v164
	v_lshlrev_b64 v[252:253], 10, v[254:255]
	v_lshl_add_u64 v[252:253], v[144:145], 0, v[252:253]
	s_not_b64 exec, exec
	v_lshl_add_u64 v[252:253], v[158:159], 0, s[16:17]
	s_mov_b64 exec, -1
	global_load_dwordx4 v[80:83], v[252:253], off
	s_mov_b64 exec, s[4:5]
	v_or_b32_e32 v254, s0, v187
	v_lshl_add_u32 v254, v254, 6, v165
	v_lshlrev_b64 v[252:253], 10, v[254:255]
	v_lshl_add_u64 v[252:253], v[144:145], 0, v[252:253]
	s_not_b64 exec, exec
	v_lshl_add_u64 v[252:253], v[156:157], 0, s[16:17]
	s_mov_b64 exec, -1
	global_load_dwordx4 v[84:87], v[252:253], off
	s_mov_b64 exec, s[6:7]
	v_or_b32_e32 v254, s0, v188
	v_lshl_add_u32 v254, v254, 6, v166
	v_lshlrev_b64 v[252:253], 10, v[254:255]
	v_lshl_add_u64 v[252:253], v[144:145], 0, v[252:253]
	s_not_b64 exec, exec
	v_lshl_add_u64 v[252:253], v[154:155], 0, s[16:17]
	s_mov_b64 exec, -1
	global_load_dwordx4 v[88:91], v[252:253], off
	s_mov_b64 exec, s[8:9]
	v_or_b32_e32 v254, s0, v189
	v_lshl_add_u32 v254, v254, 6, v167
	v_lshlrev_b64 v[252:253], 10, v[254:255]
	v_lshl_add_u64 v[252:253], v[144:145], 0, v[252:253]
	s_not_b64 exec, exec
	v_lshl_add_u64 v[252:253], v[152:153], 0, s[16:17]
	s_mov_b64 exec, -1
	global_load_dwordx4 v[108:111], v[252:253], off
	s_mov_b64 exec, s[10:11]
	v_or_b32_e32 v254, s0, v190
	v_lshl_add_u32 v254, v254, 6, v168
	v_lshlrev_b64 v[252:253], 10, v[254:255]
	v_lshl_add_u64 v[252:253], v[144:145], 0, v[252:253]
	s_not_b64 exec, exec
	v_lshl_add_u64 v[252:253], v[150:151], 0, s[16:17]
	s_mov_b64 exec, -1
	global_load_dwordx4 v[112:115], v[252:253], off
.Lmla_l0_noload:
	s_waitcnt lgkmcnt(2)
	v_mfma_f32_32x32x16_bf16 v[32:47], v[10:13], v[222:225], v[32:47]
	s_waitcnt lgkmcnt(0)
	v_mfma_f32_32x32x16_bf16 v[16:31], v[140:143], v[222:225], v[16:31]
	s_xor_b32 s18, s18, 1
	s_addk_i32 s19, 0x80
	s_add_u32 s12, s12, 0x30000
	s_addc_u32 s13, s13, 0
	s_add_i32 s61, s61, 1
	s_waitcnt lgkmcnt(0)
	s_barrier
	s_add_i32 s0, s19, 64
	s_cmp_le_i32 s0, s67
	s_cbranch_scc0 .LBB0_594
	s_add_i32 s76, s76, 1
	s_branch .Lmla_fast_l0

.Lmla_l1_negm_ok:
	s_nop 1
	s_waitcnt lgkmcnt(3)
	v_mfma_f32_32x32x16_bf16 v[64:79], v[2:5], v[92:95], v[124:139]
	ds_read_b128 v[234:237], v14 offset:128
	s_waitcnt lgkmcnt(3)
	v_mfma_f32_32x32x16_bf16 v[64:79], v[6:9], v[96:99], v[64:79]
	ds_read_b128 v[240:243], v14 offset:160
	s_waitcnt lgkmcnt(3)
	v_mfma_f32_32x32x16_bf16 v[64:79], v[10:13], v[100:103], v[64:79]
	ds_read_b128 v[2:5], v14 offset:6656
	s_waitcnt lgkmcnt(3)
	v_mfma_f32_32x32x16_bf16 v[64:79], v[140:143], v[104:107], v[64:79]
	ds_read_b128 v[6:9], v14 offset:6688
	s_waitcnt lgkmcnt(3)
	v_mfma_f32_32x32x16_bf16 v[64:79], v[234:237], v[116:119], v[64:79]
	ds_read_b128 v[10:13], v14 offset:6720
	s_waitcnt lgkmcnt(3)
	v_mfma_f32_32x32x16_bf16 v[64:79], v[240:243], v[120:123], v[64:79]
	ds_read_b128 v[140:143], v14 offset:6752
	s_waitcnt lgkmcnt(3)
	v_mfma_f32_32x32x16_bf16 v[48:63], v[2:5], v[92:95], v[124:139]
	ds_read_b128 v[234:237], v14 offset:6784
	s_waitcnt lgkmcnt(3)
	v_mfma_f32_32x32x16_bf16 v[48:63], v[6:9], v[96:99], v[48:63]
	ds_read_b128 v[240:243], v14 offset:6816
	s_waitcnt lgkmcnt(3)
	v_mfma_f32_32x32x16_bf16 v[48:63], v[10:13], v[100:103], v[48:63]
	ds_read_b128 v[2:5], v14 offset:21504
	s_waitcnt lgkmcnt(3)
	v_mfma_f32_32x32x16_bf16 v[48:63], v[140:143], v[104:107], v[48:63]
	ds_read_b128 v[6:9], v14 offset:21536
	s_waitcnt lgkmcnt(3)
	v_mfma_f32_32x32x16_bf16 v[48:63], v[234:237], v[116:119], v[48:63]
	ds_read_b128 v[10:13], v14 offset:21568
	s_waitcnt lgkmcnt(3)
	v_mfma_f32_32x32x16_bf16 v[48:63], v[240:243], v[120:123], v[48:63]
	ds_read_b128 v[140:143], v14 offset:21600
	v_exp_f32_e32 v64, v64
	v_exp_f32_e32 v65, v65
	s_waitcnt lgkmcnt(3)
	v_mfma_f32_32x32x16_bf16 v[202:217], v[2:5], v[92:95], v[124:139]
	ds_read_b128 v[234:237], v14 offset:21632
	v_exp_f32_e32 v66, v66
	v_exp_f32_e32 v67, v67
	v_exp_f32_e32 v68, v68
	v_exp_f32_e32 v69, v69
	v_exp_f32_e32 v70, v70
	s_waitcnt lgkmcnt(3)
	v_mfma_f32_32x32x16_bf16 v[202:217], v[6:9], v[96:99], v[202:217]
	ds_read_b128 v[240:243], v14 offset:21664
	v_exp_f32_e32 v71, v71
	v_pk_add_f32 v[246:247], v[64:65], v[66:67]
	v_exp_f32_e32 v72, v72
	v_exp_f32_e32 v73, v73
	v_exp_f32_e32 v74, v74
	s_waitcnt lgkmcnt(3)
	v_mfma_f32_32x32x16_bf16 v[202:217], v[10:13], v[100:103], v[202:217]
	ds_read_b128 v[2:5], v14 offset:28160
	v_exp_f32_e32 v75, v75
	v_pk_add_f32 v[248:249], v[68:69], v[70:71]
	v_exp_f32_e32 v76, v76
	v_exp_f32_e32 v77, v77
	v_pk_add_f32 v[246:247], v[246:247], v[72:73]
	s_waitcnt lgkmcnt(3)
	v_mfma_f32_32x32x16_bf16 v[202:217], v[140:143], v[104:107], v[202:217]
	ds_read_b128 v[6:9], v14 offset:28192
	v_exp_f32_e32 v78, v78
	v_exp_f32_e32 v79, v79
	v_pk_add_f32 v[248:249], v[248:249], v[74:75]
	v_exp_f32_e32 v48, v48
	v_exp_f32_e32 v49, v49
	s_waitcnt lgkmcnt(3)
	v_mfma_f32_32x32x16_bf16 v[202:217], v[234:237], v[116:119], v[202:217]
	ds_read_b128 v[10:13], v14 offset:28224
	v_pk_add_f32 v[246:247], v[246:247], v[76:77]
	v_exp_f32_e32 v50, v50
	v_exp_f32_e32 v51, v51
	v_pk_add_f32 v[248:249], v[248:249], v[78:79]
	v_exp_f32_e32 v52, v52
	s_waitcnt lgkmcnt(3)
	v_mfma_f32_32x32x16_bf16 v[202:217], v[240:243], v[120:123], v[202:217]
	ds_read_b128 v[140:143], v14 offset:28256
	v_exp_f32_e32 v53, v53
	v_pk_add_f32 v[246:247], v[246:247], v[48:49]
	v_exp_f32_e32 v54, v54
	v_exp_f32_e32 v55, v55
	v_pk_add_f32 v[248:249], v[248:249], v[50:51]
	s_waitcnt lgkmcnt(3)
	v_mfma_f32_32x32x16_bf16 v[218:233], v[2:5], v[92:95], v[124:139]
	ds_read_b128 v[234:237], v14 offset:28288
	v_exp_f32_e32 v56, v56
	v_exp_f32_e32 v57, v57
	v_pk_add_f32 v[246:247], v[246:247], v[52:53]
	v_exp_f32_e32 v58, v58
	v_exp_f32_e32 v59, v59
	s_waitcnt lgkmcnt(3)
	v_mfma_f32_32x32x16_bf16 v[218:233], v[6:9], v[96:99], v[218:233]
	ds_read_b128 v[240:243], v14 offset:28320
	v_pk_add_f32 v[248:249], v[248:249], v[54:55]
	v_exp_f32_e32 v60, v60
	v_exp_f32_e32 v61, v61
	v_pk_add_f32 v[246:247], v[246:247], v[56:57]
	v_exp_f32_e32 v62, v62
	s_waitcnt lgkmcnt(3)
	v_mfma_f32_32x32x16_bf16 v[218:233], v[10:13], v[100:103], v[218:233]
	ds_read_b64_tr_b16 v[2:3], v0 offset:13312
	ds_read_b64_tr_b16 v[4:5], v0 offset:13824
	v_exp_f32_e32 v63, v63
	v_pk_add_f32 v[248:249], v[248:249], v[58:59]
	v_pk_add_f32 v[246:247], v[246:247], v[60:61]
	v_pk_add_f32 v[248:249], v[248:249], v[62:63]
	v_pk_add_f32 v[246:247], v[246:247], v[248:249]
	s_waitcnt lgkmcnt(4)
	v_mfma_f32_32x32x16_bf16 v[218:233], v[140:143], v[104:107], v[218:233]
	ds_read_b64_tr_b16 v[6:7], v0 offset:17408
	ds_read_b64_tr_b16 v[8:9], v0 offset:17920
	v_add_f32_e32 v250, v246, v247
	v_cmp_ngt_f32_e32 vcc, 0x43800000, v250
	s_cbranch_vccnz .Lmla_l1_fbA
	v_add_f32_e32 v200, v200, v250
	v_cvt_pk_bf16_f32 v64, v64, v65
	v_cvt_pk_bf16_f32 v65, v66, v67
	s_waitcnt lgkmcnt(5)
	v_mfma_f32_32x32x16_bf16 v[218:233], v[234:237], v[116:119], v[218:233]
	ds_read_b64_tr_b16 v[10:11], v0 offset:14336
	ds_read_b64_tr_b16 v[12:13], v0 offset:14848
	v_cvt_pk_bf16_f32 v66, v68, v69
	v_cvt_pk_bf16_f32 v67, v70, v71
	v_cvt_pk_bf16_f32 v68, v72, v73
	v_cvt_pk_bf16_f32 v69, v74, v75
	v_cvt_pk_bf16_f32 v70, v76, v77
	s_waitcnt lgkmcnt(6)
	v_mfma_f32_32x32x16_bf16 v[218:233], v[240:243], v[120:123], v[218:233]
	ds_read_b64_tr_b16 v[140:141], v0 offset:18432
	ds_read_b64_tr_b16 v[142:143], v0 offset:18944
	v_cvt_pk_bf16_f32 v71, v78, v79
	v_cvt_pk_bf16_f32 v48, v48, v49
	v_cvt_pk_bf16_f32 v49, v50, v51
	v_cvt_pk_bf16_f32 v50, v52, v53
	v_cvt_pk_bf16_f32 v51, v54, v55
	v_cvt_pk_bf16_f32 v52, v56, v57
	v_cvt_pk_bf16_f32 v53, v58, v59
	v_cvt_pk_bf16_f32 v54, v60, v61
	v_cvt_pk_bf16_f32 v55, v62, v63
	v_exp_f32_e32 v202, v202
	v_exp_f32_e32 v203, v203
	s_waitcnt lgkmcnt(6)
	v_mfma_f32_32x32x16_bf16 v[32:47], v[2:5], v[64:67], v[32:47]
	ds_read_b64_tr_b16 v[234:235], v0 offset:15360
	ds_read_b64_tr_b16 v[236:237], v0 offset:15872
	v_exp_f32_e32 v204, v204
	v_exp_f32_e32 v205, v205
	v_exp_f32_e32 v206, v206
	v_exp_f32_e32 v207, v207
	v_exp_f32_e32 v208, v208
	s_waitcnt lgkmcnt(6)
	v_mfma_f32_32x32x16_bf16 v[16:31], v[6:9], v[64:67], v[16:31]
	ds_read_b64_tr_b16 v[240:241], v0 offset:19456
	ds_read_b64_tr_b16 v[242:243], v0 offset:19968
	v_exp_f32_e32 v209, v209
	v_pk_add_f32 v[246:247], v[202:203], v[204:205]
	v_exp_f32_e32 v210, v210
	v_exp_f32_e32 v211, v211
	v_exp_f32_e32 v212, v212
	s_waitcnt lgkmcnt(6)
	v_mfma_f32_32x32x16_bf16 v[32:47], v[10:13], v[68:71], v[32:47]
	ds_read_b64_tr_b16 v[2:3], v0 offset:16384
	ds_read_b64_tr_b16 v[4:5], v0 offset:16896
	v_exp_f32_e32 v213, v213
	v_pk_add_f32 v[248:249], v[206:207], v[208:209]
	v_exp_f32_e32 v214, v214
	v_exp_f32_e32 v215, v215
	v_pk_add_f32 v[246:247], v[246:247], v[210:211]
	s_waitcnt lgkmcnt(6)
	v_mfma_f32_32x32x16_bf16 v[16:31], v[140:143], v[68:71], v[16:31]
	ds_read_b64_tr_b16 v[6:7], v0 offset:20480
	ds_read_b64_tr_b16 v[8:9], v0 offset:20992
	v_exp_f32_e32 v216, v216
	v_exp_f32_e32 v217, v217
	v_pk_add_f32 v[248:249], v[248:249], v[212:213]
	v_exp_f32_e32 v218, v218
	v_exp_f32_e32 v219, v219
	s_waitcnt lgkmcnt(6)
	v_mfma_f32_32x32x16_bf16 v[32:47], v[234:237], v[48:51], v[32:47]
	ds_read_b64_tr_b16 v[10:11], v0 offset:34816
	ds_read_b64_tr_b16 v[12:13], v0 offset:35328
	v_pk_add_f32 v[246:247], v[246:247], v[214:215]
	v_exp_f32_e32 v220, v220
	v_exp_f32_e32 v221, v221
	v_pk_add_f32 v[248:249], v[248:249], v[216:217]
	v_exp_f32_e32 v222, v222
	s_waitcnt lgkmcnt(6)
	v_mfma_f32_32x32x16_bf16 v[16:31], v[240:243], v[48:51], v[16:31]
	ds_read_b64_tr_b16 v[140:141], v0 offset:38912
	ds_read_b64_tr_b16 v[142:143], v0 offset:39424
	v_exp_f32_e32 v223, v223
	v_pk_add_f32 v[246:247], v[246:247], v[218:219]
	v_exp_f32_e32 v224, v224
	v_exp_f32_e32 v225, v225
	v_pk_add_f32 v[248:249], v[248:249], v[220:221]
	s_waitcnt lgkmcnt(6)
	v_mfma_f32_32x32x16_bf16 v[32:47], v[2:5], v[52:55], v[32:47]
	ds_read_b64_tr_b16 v[234:235], v0 offset:35840
	ds_read_b64_tr_b16 v[236:237], v0 offset:36352
	v_exp_f32_e32 v226, v226
	v_exp_f32_e32 v227, v227
	v_pk_add_f32 v[246:247], v[246:247], v[222:223]
	v_exp_f32_e32 v228, v228
	v_exp_f32_e32 v229, v229
	s_waitcnt lgkmcnt(6)
	v_mfma_f32_32x32x16_bf16 v[16:31], v[6:9], v[52:55], v[16:31]
	ds_read_b64_tr_b16 v[240:241], v0 offset:39936
	ds_read_b64_tr_b16 v[242:243], v0 offset:40448
	v_pk_add_f32 v[248:249], v[248:249], v[224:225]
	v_exp_f32_e32 v230, v230
	v_exp_f32_e32 v231, v231
	v_pk_add_f32 v[246:247], v[246:247], v[226:227]
	v_exp_f32_e32 v232, v232
	v_exp_f32_e32 v233, v233
	v_pk_add_f32 v[248:249], v[248:249], v[228:229]
	v_pk_add_f32 v[246:247], v[246:247], v[230:231]
	v_pk_add_f32 v[248:249], v[248:249], v[232:233]
	v_pk_add_f32 v[246:247], v[246:247], v[248:249]
	v_add_f32_e32 v250, v246, v247
	v_cmp_ngt_f32_e32 vcc, 0x43800000, v250
	s_cbranch_vccnz .Lmla_l1_fbB
	v_add_f32_e32 v200, v200, v250
	v_cvt_pk_bf16_f32 v202, v202, v203
	v_cvt_pk_bf16_f32 v203, v204, v205
	v_cvt_pk_bf16_f32 v204, v206, v207
	v_cvt_pk_bf16_f32 v205, v208, v209
	v_cvt_pk_bf16_f32 v206, v210, v211
	v_cvt_pk_bf16_f32 v207, v212, v213
	v_cvt_pk_bf16_f32 v208, v214, v215
	v_cvt_pk_bf16_f32 v209, v216, v217
	v_cvt_pk_bf16_f32 v218, v218, v219
	v_cvt_pk_bf16_f32 v219, v220, v221
	v_cvt_pk_bf16_f32 v220, v222, v223
	v_cvt_pk_bf16_f32 v221, v224, v225
	v_cvt_pk_bf16_f32 v222, v226, v227
	v_cvt_pk_bf16_f32 v223, v228, v229
	v_cvt_pk_bf16_f32 v224, v230, v231
	v_cvt_pk_bf16_f32 v225, v232, v233
	s_waitcnt lgkmcnt(6)
	v_mfma_f32_32x32x16_bf16 v[32:47], v[10:13], v[202:205], v[32:47]
	ds_read_b64_tr_b16 v[2:3], v0 offset:36864
	ds_read_b64_tr_b16 v[4:5], v0 offset:37376
	s_waitcnt vmcnt(0)
	s_xor_b32 s16, s18, 1
	s_mul_i32 s16, s16, 0xa800
	v_add_u32_e32 v254, s16, v170
	s_mov_b64 exec, s[2:3]
	v_add_u32_e32 v254, v254, v149
	v_add3_u32 v254, v254, v171, v169
	v_add_u32_e32 v254, 0x1c00, v254
	s_not_b64 exec, exec
	v_add3_u32 v254, v254, v192, v193
	s_mov_b64 exec, -1
	ds_write_b128 v254, v[80:83]
	v_add_u32_e32 v254, s16, v172
	s_mov_b64 exec, s[4:5]
	v_add_u32_e32 v254, v254, v149
	v_add3_u32 v254, v254, v173, v169
	v_add_u32_e32 v254, 0x1c00, v254
	s_not_b64 exec, exec
	v_add3_u32 v254, v254, v194, v195
	s_mov_b64 exec, -1
	ds_write_b128 v254, v[84:87]
	v_add_u32_e32 v254, s16, v174
	s_mov_b64 exec, s[6:7]
	v_add_u32_e32 v254, v254, v149
	v_add3_u32 v254, v254, v175, v169
	v_add_u32_e32 v254, 0x1c00, v254
	s_not_b64 exec, exec
	v_add3_u32 v254, v254, v196, v197
	s_mov_b64 exec, -1
	ds_write_b128 v254, v[88:91]
	v_add_u32_e32 v254, s16, v176
	s_mov_b64 exec, s[8:9]
	v_add_u32_e32 v254, v254, v149
	v_add3_u32 v254, v254, v177, v169
	v_add_u32_e32 v254, 0x1c00, v254
	s_not_b64 exec, exec
	v_add3_u32 v254, v254, v198, v199
	s_mov_b64 exec, -1
	ds_write_b128 v254, v[108:111]
	v_add_u32_e32 v254, s16, v178
	s_mov_b64 exec, s[10:11]
	v_add_u32_e32 v254, v254, v149
	v_add3_u32 v254, v254, v179, v169
	v_add_u32_e32 v254, 0x1c00, v254
	s_not_b64 exec, exec
	v_add3_u32 v254, v254, v180, v181
	s_mov_b64 exec, -1
	ds_write_b128 v254, v[112:115]
	s_waitcnt lgkmcnt(11)
	v_mfma_f32_32x32x16_bf16 v[16:31], v[140:143], v[202:205], v[16:31]
	ds_read_b64_tr_b16 v[6:7], v0 offset:40960
	ds_read_b64_tr_b16 v[8:9], v0 offset:41472
	s_waitcnt lgkmcnt(11)
	v_mfma_f32_32x32x16_bf16 v[32:47], v[234:237], v[206:209], v[32:47]
	ds_read_b64_tr_b16 v[10:11], v0 offset:37888
	ds_read_b64_tr_b16 v[12:13], v0 offset:38400
	s_waitcnt lgkmcnt(11)
	v_mfma_f32_32x32x16_bf16 v[16:31], v[240:243], v[206:209], v[16:31]
	ds_read_b64_tr_b16 v[140:141], v0 offset:41984
	ds_read_b64_tr_b16 v[142:143], v0 offset:42496
	s_waitcnt lgkmcnt(11)
	v_mfma_f32_32x32x16_bf16 v[32:47], v[2:5], v[218:221], v[32:47]
	s_waitcnt lgkmcnt(4)
	v_mfma_f32_32x32x16_bf16 v[16:31], v[6:9], v[218:221], v[16:31]
	s_add_i32 s0, s19, 0xc0
	s_cmp_le_i32 s0, s84
	s_cbranch_scc0 .Lmla_l1_noload
	s_add_u32 s16, s12, 0x30000
	s_addc_u32 s17, s13, 0
	s_add_i32 s0, s94, 1
	s_lshl_b32 s0, s0, 1
	v_mov_b32_e32 v255, 0
	s_mov_b64 exec, s[2:3]
	v_or_b32_e32 v254, s0, v186
	v_lshl_add_u32 v254, v254, 6, v164
	v_lshlrev_b64 v[252:253], 10, v[254:255]
	v_lshl_add_u64 v[252:253], v[144:145], 0, v[252:253]
	s_not_b64 exec, exec
	v_lshl_add_u64 v[252:253], v[158:159], 0, s[16:17]
	s_mov_b64 exec, -1
	global_load_dwordx4 v[80:83], v[252:253], off
	s_mov_b64 exec, s[4:5]
	v_or_b32_e32 v254, s0, v187
	v_lshl_add_u32 v254, v254, 6, v165
	v_lshlrev_b64 v[252:253], 10, v[254:255]
	v_lshl_add_u64 v[252:253], v[144:145], 0, v[252:253]
	s_not_b64 exec, exec
	v_lshl_add_u64 v[252:253], v[156:157], 0, s[16:17]
	s_mov_b64 exec, -1
	global_load_dwordx4 v[84:87], v[252:253], off
	s_mov_b64 exec, s[6:7]
	v_or_b32_e32 v254, s0, v188
	v_lshl_add_u32 v254, v254, 6, v166
	v_lshlrev_b64 v[252:253], 10, v[254:255]
	v_lshl_add_u64 v[252:253], v[144:145], 0, v[252:253]
	s_not_b64 exec, exec
	v_lshl_add_u64 v[252:253], v[154:155], 0, s[16:17]
	s_mov_b64 exec, -1
	global_load_dwordx4 v[88:91], v[252:253], off
	s_mov_b64 exec, s[8:9]
	v_or_b32_e32 v254, s0, v189
	v_lshl_add_u32 v254, v254, 6, v167
	v_lshlrev_b64 v[252:253], 10, v[254:255]
	v_lshl_add_u64 v[252:253], v[144:145], 0, v[252:253]
	s_not_b64 exec, exec
	v_lshl_add_u64 v[252:253], v[152:153], 0, s[16:17]
	s_mov_b64 exec, -1
	global_load_dwordx4 v[108:111], v[252:253], off
	s_mov_b64 exec, s[10:11]
	v_or_b32_e32 v254, s0, v190
	v_lshl_add_u32 v254, v254, 6, v168
	v_lshlrev_b64 v[252:253], 10, v[254:255]
	v_lshl_add_u64 v[252:253], v[144:145], 0, v[252:253]
	s_not_b64 exec, exec
	v_lshl_add_u64 v[252:253], v[150:151], 0, s[16:17]
	s_mov_b64 exec, -1
	global_load_dwordx4 v[112:115], v[252:253], off
.Lmla_l1_noload:
	s_waitcnt lgkmcnt(2)
	v_mfma_f32_32x32x16_bf16 v[32:47], v[10:13], v[222:225], v[32:47]
	s_waitcnt lgkmcnt(0)
	v_mfma_f32_32x32x16_bf16 v[16:31], v[140:143], v[222:225], v[16:31]
	s_xor_b32 s18, s18, 1
	s_addk_i32 s19, 0x80
	s_add_u32 s12, s12, 0x30000
	s_addc_u32 s13, s13, 0
	s_add_i32 s63, s63, 1
	s_waitcnt lgkmcnt(0)
	s_barrier
	s_add_i32 s0, s19, 64
	s_cmp_le_i32 s0, s84
	s_cbranch_scc0 .LBB0_1884
	s_add_i32 s94, s94, 1
	s_branch .Lmla_fast_l1
